# t19 + FoX scan dependency counter prefetched during the kv-up store drain; no invalidate when no wait was needed
# baseline (speedup 1.0000x reference)
.LBB0_457:
	v_mov_b32_e32 v2, 0x3900
	global_load_dword v3, v2, s[72:73] sc1
	s_waitcnt vmcnt(0)
	s_barrier
.Lscan_hook:
	s_cmpk_ge_i32 s76, 32
	s_cbranch_scc1 .LBB0_458
	v_cmp_eq_u32_e32 vcc, 0, v161
	s_and_saveexec_b64 s[2:3], vcc
	s_cbranch_execz .Lscan_wait_done
	v_mov_b32_e32 v0, 0x3900
	s_mov_b32 s4, 0
	v_cmp_le_u32_e32 vcc, s92, v3
	s_cbranch_vccnz .Lscan_wait_done
